# v053 + DSA loop: selection-word load issued before the K/V DMA loads, end-of-iteration vmcnt(0) -> vmcnt(4)
# speedup vs baseline: 1.0028x; 1.0028x over previous
; template <int MODE>
; DI void attn_item(const u16* Qp, int ldq, const u16* Kp, int ldk, const u16* VTp, int ldv, u16* Op, int ldo,
;                   int q0, int nkt, const float* Fc, const unsigned* BM, float kmaxn, char* smem) {
;     ...
;     uint2 bwn = make_uint2(0xffffffffu, 0xffffffffu);
;     const int tn = AT_TILE(more1 ? (kt + 1) : kt);
;     float flast = 0.f;
;     if (MODE == 1) { rf = *(const f32x4*)(Fc + tn * 64 + (tid & 15) * 4); flast = Fc[tn * 64 + 63]; }
;     if (MODE == 2) bwn = *(const uint2*)(bmq + tn * 2);
;     AT_STAGE(kt + 3);
;     const bool diag = (MODE == 1) && (ts + 63 > qw);
;     float mx = -1e30f;
;     if (MODE == 1) {
; #pragma unroll
;       for (int k2 = 0; k2 < 2; ++k2)
; #pragma unroll
;         for (int j = 0; j < 4; ++j) {
;           const int kl = 32 * k2 + 16 * (j >> 1) + 8 * h + 4 * (j & 1);
;           const f32x4 f4 = *(const f32x4*)(sF + kl);
; #pragma unroll
;           for (int i = 0; i < 4; ++i) {
;             float x = sc[k2][j * 4 + i] * c1 + (fcq - f4[i]);
;             if (diag && (ts + kl + i > q)) x = -1e30f;
;             sc[k2][j * 4 + i] = x;
;             mx = fmaxf(mx, x);
;           }
;         }
;     } else {
; #pragma unroll
;       for (int k2 = 0; k2 < 2; ++k2)
; #pragma unroll
;         for (int e = 0; e < 16; ++e) mx = fmaxf(mx, sc[k2][e]);
;       mx *= c1;
;     }
;     mx = fmaxf(mx, shflx(mx, 32, lane));
;     if (__any(mx > m_run + 8.f)) {
;       const float m_new = fmaxf(m_run, mx);
;       const float alpha = __builtin_amdgcn_exp2f(m_run - m_new);
;       m_run = m_new; l_run *= alpha;
; #pragma unroll
;       for (int i = 0; i < 4; ++i)
; #pragma unroll
;         for (int e = 0; e < 16; ++e) o[i][e] *= alpha;
;     }
;     ...
;     for (int g4 = 0; g4 < 4; ++g4) {
;       const int k2 = g4 >> 1, s2 = g4 & 1;
;       const f32x16 zero16 = {0.f, 0.f, 0.f, 0.f, 0.f, 0.f, 0.f, 0.f, 0.f, 0.f, 0.f, 0.f, 0.f, 0.f, 0.f, 0.f};
; #pragma unroll
;       for (int st = s2 * 4; st < s2 * 4 + 4; ++st) {
;         bf16x8 a = *(const bf16x8*)(sKn + kro + k2 * 8192 + (((st * 2 + h) ^ ksw) << 4));
;         sn[k2] = (st == 0) ? MFMA(a, qf[st], zero16) : MFMA(a, qf[st], sn[k2]);
;       }
;       const unsigned wbits = k2 ? bw.y : bw.x;
;       float pv8[8];
; #pragma unroll
;       for (int e8 = 0; e8 < 8; ++e8) {
;         const int e = 8 * s2 + e8;
;         float pv;
;         if (MODE == 1) {
.LBB0_492:
	s_mov_b32 s15, s13
	s_add_i32 s13, s13, 1
	s_cmp_lt_i32 s13, s12
	s_cselect_b32 s16, s13, s15
	s_lshl_b32 s36, s16, 1
	s_add_i32 s15, s15, 3
	s_and_b32 s16, s14, 0x18000
	s_min_i32 s15, s15, s11
	v_add_u32_e32 v0, s16, v171
	v_lshl_add_u64 v[2:3], s[36:37], 2, v[166:167]
	global_load_dwordx2 v[2:3], v[2:3], off
	v_mad_u64_u32 v[4:5], s[16:17], s15, v210, v[162:163]
	s_lshl_b32 s36, s15, 6
	v_readfirstlane_b32 s15, v0
	v_add_u32_e32 v8, 0x2000, v0
	s_mov_b32 m0, s15
	v_readfirstlane_b32 s15, v8
	global_load_lds_dwordx4 v[4:5], off
	v_lshl_add_u64 v[4:5], v[4:5], 0, s[18:19]
	s_mov_b32 m0, s15
	v_lshl_add_u64 v[6:7], s[36:37], 1, v[164:165]
	global_load_lds_dwordx4 v[4:5], off
	v_add_u32_e32 v4, 0x4000, v0
	v_add_u32_e32 v0, 0x6000, v0
	v_readfirstlane_b32 s15, v4
	s_mov_b32 m0, s15
	v_readfirstlane_b32 s15, v0
	v_lshl_add_u64 v[4:5], v[6:7], 0, s[20:21]
	global_load_lds_dwordx4 v[6:7], off
	s_mov_b32 m0, s15
	s_mov_b32 s15, 0xf149f2ca
	global_load_lds_dwordx4 v[4:5], off
	v_max3_f32 v0, v96, s15, v97
	v_max3_f32 v0, v0, v98, v99
	v_max3_f32 v0, v0, v100, v101
	v_max3_f32 v0, v0, v102, v103
	v_max3_f32 v0, v0, v104, v105
	v_max3_f32 v0, v0, v106, v107
	v_max3_f32 v0, v0, v108, v109
	v_max3_f32 v0, v0, v110, v111
	v_max3_f32 v0, v0, v80, v81
	v_max3_f32 v0, v0, v82, v83
	v_max3_f32 v0, v0, v84, v85
	v_max3_f32 v0, v0, v86, v87
	v_max3_f32 v0, v0, v88, v89
	v_max3_f32 v0, v0, v90, v91
	v_max3_f32 v0, v0, v92, v93
	v_max3_f32 v0, v0, v94, v95
	v_mul_f32_e32 v0, 0x3e0293ee, v0
	ds_bpermute_b32 v4, v181, v0
	s_waitcnt lgkmcnt(0)
	v_max_f32_e32 v4, v4, v4
	v_max_f32_e32 v0, v0, v4
	v_add_f32_e32 v4, 0x41000000, v206
	v_cmp_gt_f32_e32 vcc, v0, v4
	s_cbranch_vccz .LBB0_494
	v_max_f32_e32 v0, v0, v0
	v_max_f32_e32 v4, v206, v206
	v_max_f32_e32 v4, v4, v0
	v_sub_f32_e32 v0, v206, v4
	v_exp_f32_e32 v0, v0
	v_mov_b32_e32 v206, v4
	v_pk_mul_f32 v[78:79], v[78:79], v[0:1] op_sel_hi:[1,0]
	v_pk_mul_f32 v[76:77], v[76:77], v[0:1] op_sel_hi:[1,0]
	v_pk_mul_f32 v[74:75], v[74:75], v[0:1] op_sel_hi:[1,0]
	v_pk_mul_f32 v[72:73], v[72:73], v[0:1] op_sel_hi:[1,0]
	v_pk_mul_f32 v[70:71], v[70:71], v[0:1] op_sel_hi:[1,0]
	v_pk_mul_f32 v[68:69], v[68:69], v[0:1] op_sel_hi:[1,0]
	v_pk_mul_f32 v[66:67], v[66:67], v[0:1] op_sel_hi:[1,0]
	v_pk_mul_f32 v[64:65], v[64:65], v[0:1] op_sel_hi:[1,0]
	v_pk_mul_f32 v[62:63], v[62:63], v[0:1] op_sel_hi:[1,0]
	v_pk_mul_f32 v[60:61], v[60:61], v[0:1] op_sel_hi:[1,0]
	v_pk_mul_f32 v[58:59], v[58:59], v[0:1] op_sel_hi:[1,0]
	v_pk_mul_f32 v[56:57], v[56:57], v[0:1] op_sel_hi:[1,0]
	v_pk_mul_f32 v[54:55], v[54:55], v[0:1] op_sel_hi:[1,0]
	v_pk_mul_f32 v[52:53], v[52:53], v[0:1] op_sel_hi:[1,0]
	v_pk_mul_f32 v[50:51], v[50:51], v[0:1] op_sel_hi:[1,0]
	v_pk_mul_f32 v[48:49], v[48:49], v[0:1] op_sel_hi:[1,0]
	v_pk_mul_f32 v[46:47], v[46:47], v[0:1] op_sel_hi:[1,0]
	v_pk_mul_f32 v[44:45], v[44:45], v[0:1] op_sel_hi:[1,0]
	v_pk_mul_f32 v[42:43], v[42:43], v[0:1] op_sel_hi:[1,0]
	v_pk_mul_f32 v[40:41], v[40:41], v[0:1] op_sel_hi:[1,0]
	v_pk_mul_f32 v[38:39], v[38:39], v[0:1] op_sel_hi:[1,0]
	v_pk_mul_f32 v[36:37], v[36:37], v[0:1] op_sel_hi:[1,0]
	v_pk_mul_f32 v[34:35], v[34:35], v[0:1] op_sel_hi:[1,0]
	v_pk_mul_f32 v[32:33], v[32:33], v[0:1] op_sel_hi:[1,0]
	v_pk_mul_f32 v[30:31], v[30:31], v[0:1] op_sel_hi:[1,0]
	v_pk_mul_f32 v[28:29], v[28:29], v[0:1] op_sel_hi:[1,0]
	v_pk_mul_f32 v[26:27], v[26:27], v[0:1] op_sel_hi:[1,0]
	v_pk_mul_f32 v[24:25], v[24:25], v[0:1] op_sel_hi:[1,0]
	v_pk_mul_f32 v[22:23], v[22:23], v[0:1] op_sel_hi:[1,0]
	v_pk_mul_f32 v[20:21], v[20:21], v[0:1] op_sel_hi:[1,0]
	v_pk_mul_f32 v[18:19], v[18:19], v[0:1] op_sel_hi:[1,0]
	v_pk_mul_f32 v[16:17], v[16:17], v[0:1] op_sel_hi:[1,0]
	v_mul_f32_e32 v182, v182, v0
.LBB0_494:
	s_add_i32 s15, s14, 0xffff0000
	s_and_b32 s15, s15, 0x18000
	v_add_u32_e32 v252, s15, v172
	s_add_i32 s15, s14, 0xfffe8000
	s_and_b32 s15, s15, 0x18000
	v_add_u32_e32 v211, s15, v204
	v_add_u32_e32 v203, v252, v173
	v_add_u32_e32 v205, v252, v174
	v_add_u32_e32 v207, v252, v175
	v_add_u32_e32 v209, v252, v176
	v_add_u32_e32 v217, v211, v190
	ds_read_b128 v[224:227], v203
	ds_read_b128 v[228:231], v205
	ds_read_b128 v[232:235], v207
	ds_read_b128 v[236:239], v209
	ds_read_b128 v[240:243], v217 offset:16384
	ds_read_b128 v[244:247], v217 offset:20480
	ds_read_b128 v[248:251], v217 offset:24576
	ds_read_b128 v[212:215], v217 offset:28672
	v_fma_f32 v0, v96, s33, -v206
	v_fma_f32 v14, v97, s33, -v206
	v_fma_f32 v96, v98, s33, -v206
	v_fma_f32 v98, v99, s33, -v206
	s_waitcnt lgkmcnt(7)
	v_mfma_f32_32x32x16_bf16 v[112:127], v[224:227], v[128:131], 0
	v_add_u32_e32 v216, v252, v177
	ds_read_b128 v[224:227], v216
	v_fma_f32 v100, v100, s33, -v206
	v_exp_f32_e32 v14, v14
	v_exp_f32_e32 v98, v98
	v_fma_f32 v101, v101, s33, -v206
	v_exp_f32_e32 v96, v96
	s_waitcnt lgkmcnt(7)
	v_mfma_f32_32x32x16_bf16 v[112:127], v[228:231], v[132:135], v[112:127]
	v_add_u32_e32 v216, v252, v178
	ds_read_b128 v[228:231], v216
	v_bfe_i32 v15, v168, v183, 1
	v_bfe_i32 v99, v168, v185, 1
	v_exp_f32_e32 v208, v0
	v_and_b32_e32 v14, v15, v14
	s_waitcnt lgkmcnt(7)
	v_mfma_f32_32x32x16_bf16 v[112:127], v[232:235], v[136:139], v[112:127]
	v_add_u32_e32 v216, v252, v179
	ds_read_b128 v[232:235], v216
	v_exp_f32_e32 v4, v100
	v_exp_f32_e32 v5, v101
	v_bfe_i32 v6, v168, v186, 1
	v_and_b32_e32 v15, v99, v98
	v_and_b32_e32 v98, v6, v4
	v_fma_f32 v4, v102, s33, -v206
	v_bfe_i32 v97, v168, v184, 1
	s_waitcnt lgkmcnt(7)
; #define MFMA(a, b, c) __builtin_amdgcn_mfma_f32_32x32x16_bf16((a), (b), (c), 0, 0, 0)
; template <int MODE>
; DI void attn_item(const u16* Qp, int ldq, const u16* Kp, int ldk, const u16* VTp, int ldv, u16* Op, int ldo,
;                   int q0, int nkt, const float* Fc, const unsigned* BM, float kmaxn, char* smem) {
;     ...
;     for (int g4 = 0; g4 < 4; ++g4) {
;       const int k2 = g4 >> 1, s2 = g4 & 1;
;       const f32x16 zero16 = {0.f, 0.f, 0.f, 0.f, 0.f, 0.f, 0.f, 0.f, 0.f, 0.f, 0.f, 0.f, 0.f, 0.f, 0.f, 0.f};
; #pragma unroll
;       for (int st = s2 * 4; st < s2 * 4 + 4; ++st) {
;         bf16x8 a = *(const bf16x8*)(sKn + kro + k2 * 8192 + (((st * 2 + h) ^ ksw) << 4));
;         sn[k2] = (st == 0) ? MFMA(a, qf[st], zero16) : MFMA(a, qf[st], sn[k2]);
;       }
;       const unsigned wbits = k2 ? bw.y : bw.x;
;       float pv8[8];
; #pragma unroll
;       for (int e8 = 0; e8 < 8; ++e8) {
;         const int e = 8 * s2 + e8;
;         float pv;
;         if (MODE == 1) {
;           const float x = sc[k2][e];
;           pv = __builtin_amdgcn_exp2f(x - m_run);
;           if (diag) pv = (x <= -1e29f) ? 0.f : pv;
;         } else {
;           pv = __builtin_amdgcn_exp2f(sc[k2][e] * c1 - m_run);
;           if (MODE == 2) {
;             const int kb = 16 * ((e >> 2) >> 1) + 8 * h + 4 * ((e >> 2) & 1) + (e & 3);
;             const int msk = __builtin_amdgcn_sbfe(wbits, kb, 1);
;             pv = __int_as_float(__float_as_int(pv) & msk);
;           }
;         }
;         pv8[e8] = pv; ps += pv;
;       }
;       u32x4 u;
;       u[0] = pk2(pv8[0], pv8[1]); u[1] = pk2(pv8[2], pv8[3]); u[2] = pk2(pv8[4], pv8[5]); u[3] = pk2(pv8[6], pv8[7]);
;       const bf16x8 pfg = __builtin_bit_cast(bf16x8, u);
; #pragma unroll
;       for (int dt = 0; dt < 4; ++dt) {
;         bf16x8 a = *(const bf16x8*)(sV + vro + dt * 4096 + (((4 * k2 + 2 * s2 + h) ^ vsw) << 4));
;         o[dt] = MFMA(a, pfg, o[dt]);
;       }
	v_mfma_f32_32x32x16_bf16 v[112:127], v[236:239], v[140:143], v[112:127]
	v_add_u32_e32 v216, v252, v180
	ds_read_b128 v[236:239], v216
	v_bfe_i32 v7, v168, v187, 1
	v_exp_f32_e32 v8, v4
	v_fma_f32 v4, v103, s33, -v206
	v_and_b32_e32 v96, v97, v96
	v_and_b32_e32 v97, v7, v5
	v_exp_f32_e32 v9, v4
	v_bfe_i32 v13, v168, v170, 1
	v_bfe_i32 v10, v168, v188, 1
	v_bfe_i32 v11, v168, v189, 1
	v_and_b32_e32 v13, v13, v208
	v_and_b32_e32 v100, v11, v9
	v_and_b32_e32 v101, v10, v8
	v_cvt_pk_bf16_f32 v8, v13, v14
	v_cvt_pk_bf16_f32 v9, v96, v15
	v_cvt_pk_bf16_f32 v10, v98, v97
	v_cvt_pk_bf16_f32 v11, v101, v100
	v_add_u32_e32 v217, v211, v199
	s_waitcnt lgkmcnt(7)
	s_nop 0
	v_mfma_f32_32x32x16_bf16 v[64:79], v[240:243], v[8:11], v[64:79]
	ds_read_b128 v[240:243], v217 offset:16384
	v_add_f32_e32 v4, 0, v13
	v_add_f32_e32 v4, v4, v14
	s_waitcnt lgkmcnt(7)
	v_mfma_f32_32x32x16_bf16 v[48:63], v[244:247], v[8:11], v[48:63]
	ds_read_b128 v[244:247], v217 offset:20480
	v_add_f32_e32 v4, v4, v96
	v_add_f32_e32 v4, v4, v15
	s_waitcnt lgkmcnt(7)
	v_mfma_f32_32x32x16_bf16 v[32:47], v[248:251], v[8:11], v[32:47]
	ds_read_b128 v[248:251], v217 offset:24576
	v_add_f32_e32 v4, v4, v98
	v_add_f32_e32 v4, v4, v97
	s_waitcnt lgkmcnt(7)
	v_mfma_f32_32x32x16_bf16 v[16:31], v[212:215], v[8:11], v[16:31]
	ds_read_b128 v[212:215], v217 offset:28672
	v_add_f32_e32 v4, v4, v101
	v_add_f32_e32 v96, v4, v100
	s_waitcnt lgkmcnt(7)
	v_mfma_f32_32x32x16_bf16 v[112:127], v[224:227], v[144:147], v[112:127]
	ds_read_b128 v[224:227], v203 offset:8192
	v_fma_f32 v8, v104, s33, -v206
	v_fma_f32 v10, v105, s33, -v206
	v_exp_f32_e32 v8, v8
	v_exp_f32_e32 v10, v10
	v_bfe_i32 v9, v168, v191, 1
	v_bfe_i32 v11, v168, v192, 1
	v_and_b32_e32 v98, v9, v8
	v_and_b32_e32 v97, v11, v10
	s_waitcnt lgkmcnt(7)
	v_mfma_f32_32x32x16_bf16 v[112:127], v[228:231], v[148:151], v[112:127]
	ds_read_b128 v[228:231], v205 offset:8192
	v_fma_f32 v8, v106, s33, -v206
	v_fma_f32 v10, v107, s33, -v206
	v_exp_f32_e32 v8, v8
	v_exp_f32_e32 v10, v10
	v_bfe_i32 v9, v168, v193, 1
	v_bfe_i32 v11, v168, v194, 1
	v_and_b32_e32 v100, v9, v8
	v_and_b32_e32 v99, v11, v10
	s_waitcnt lgkmcnt(7)
	v_mfma_f32_32x32x16_bf16 v[112:127], v[232:235], v[152:155], v[112:127]
	ds_read_b128 v[232:235], v207 offset:8192
	v_fma_f32 v8, v108, s33, -v206
	v_fma_f32 v10, v109, s33, -v206
	v_exp_f32_e32 v8, v8
	v_exp_f32_e32 v10, v10
	v_bfe_i32 v9, v168, v195, 1
	v_bfe_i32 v11, v168, v196, 1
	v_and_b32_e32 v101, v11, v10
	v_and_b32_e32 v102, v9, v8
	s_waitcnt lgkmcnt(7)
	v_mfma_f32_32x32x16_bf16 v[112:127], v[236:239], v[156:159], v[112:127]
	ds_read_b128 v[236:239], v209 offset:8192
	v_fma_f32 v8, v110, s33, -v206
	v_fma_f32 v10, v111, s33, -v206
	v_exp_f32_e32 v8, v8
	v_exp_f32_e32 v10, v10
	v_bfe_i32 v9, v168, v197, 1
	v_bfe_i32 v11, v168, v198, 1
	v_and_b32_e32 v104, v9, v8
	v_and_b32_e32 v103, v11, v10
	v_cvt_pk_bf16_f32 v8, v98, v97
	v_cvt_pk_bf16_f32 v9, v100, v99
	v_cvt_pk_bf16_f32 v10, v102, v101
	v_cvt_pk_bf16_f32 v11, v104, v103
	v_add_u32_e32 v217, v211, v200
	s_waitcnt lgkmcnt(7)
	s_nop 0
	v_mfma_f32_32x32x16_bf16 v[64:79], v[240:243], v[8:11], v[64:79]
	ds_read_b128 v[240:243], v217 offset:16384
	v_add_f32_e32 v253, v96, v98
	v_add_f32_e32 v253, v253, v97
	s_waitcnt lgkmcnt(7)
	v_mfma_f32_32x32x16_bf16 v[48:63], v[244:247], v[8:11], v[48:63]
	ds_read_b128 v[244:247], v217 offset:20480
	v_add_f32_e32 v253, v253, v100
	v_add_f32_e32 v253, v253, v99
	s_waitcnt lgkmcnt(7)
	v_mfma_f32_32x32x16_bf16 v[32:47], v[248:251], v[8:11], v[32:47]
	ds_read_b128 v[248:251], v217 offset:24576
	v_add_f32_e32 v253, v253, v102
	v_add_f32_e32 v253, v253, v101
	s_waitcnt lgkmcnt(7)
	v_mfma_f32_32x32x16_bf16 v[16:31], v[212:215], v[8:11], v[16:31]
	ds_read_b128 v[212:215], v217 offset:28672
	v_add_f32_e32 v253, v253, v104
	v_add_f32_e32 v168, v253, v103
	s_waitcnt lgkmcnt(7)
	v_mfma_f32_32x32x16_bf16 v[96:111], v[224:227], v[128:131], 0
	v_add_u32_e32 v216, v252, v177
	ds_read_b128 v[224:227], v216 offset:8192
	v_fma_f32 v8, v80, s33, -v206
	v_fma_f32 v10, v81, s33, -v206
	v_exp_f32_e32 v8, v8
	v_exp_f32_e32 v10, v10
	v_bfe_i32 v9, v169, v170, 1
	v_bfe_i32 v11, v169, v183, 1
	v_and_b32_e32 v81, v9, v8
	v_and_b32_e32 v80, v11, v10
	s_waitcnt lgkmcnt(7)
	v_mfma_f32_32x32x16_bf16 v[96:111], v[228:231], v[132:135], v[96:111]
	v_add_u32_e32 v216, v252, v178
	ds_read_b128 v[228:231], v216 offset:8192
	v_fma_f32 v8, v82, s33, -v206
	v_fma_f32 v10, v83, s33, -v206
	v_exp_f32_e32 v8, v8
	v_exp_f32_e32 v10, v10
	v_bfe_i32 v9, v169, v184, 1
	v_bfe_i32 v11, v169, v185, 1
	v_and_b32_e32 v83, v9, v8
	v_and_b32_e32 v82, v11, v10
	s_waitcnt lgkmcnt(7)
; template <int MODE>
; DI void attn_item(const u16* Qp, int ldq, const u16* Kp, int ldk, const u16* VTp, int ldv, u16* Op, int ldo,
;                   int q0, int nkt, const float* Fc, const unsigned* BM, float kmaxn, char* smem) {
;     ...
;     for (int g4 = 0; g4 < 4; ++g4) {
;       const int k2 = g4 >> 1, s2 = g4 & 1;
;       const f32x16 zero16 = {0.f, 0.f, 0.f, 0.f, 0.f, 0.f, 0.f, 0.f, 0.f, 0.f, 0.f, 0.f, 0.f, 0.f, 0.f, 0.f};
; #pragma unroll
;       for (int st = s2 * 4; st < s2 * 4 + 4; ++st) {
;         bf16x8 a = *(const bf16x8*)(sKn + kro + k2 * 8192 + (((st * 2 + h) ^ ksw) << 4));
;         sn[k2] = (st == 0) ? MFMA(a, qf[st], zero16) : MFMA(a, qf[st], sn[k2]);
;       }
;       const unsigned wbits = k2 ? bw.y : bw.x;
;       float pv8[8];
; #pragma unroll
;       for (int e8 = 0; e8 < 8; ++e8) {
;         const int e = 8 * s2 + e8;
;         float pv;
;         if (MODE == 1) {
;           const float x = sc[k2][e];
;           pv = __builtin_amdgcn_exp2f(x - m_run);
;           if (diag) pv = (x <= -1e29f) ? 0.f : pv;
;         } else {
;           pv = __builtin_amdgcn_exp2f(sc[k2][e] * c1 - m_run);
;           if (MODE == 2) {
;             const int kb = 16 * ((e >> 2) >> 1) + 8 * h + 4 * ((e >> 2) & 1) + (e & 3);
;             const int msk = __builtin_amdgcn_sbfe(wbits, kb, 1);
;             pv = __int_as_float(__float_as_int(pv) & msk);
;           }
;         }
;         pv8[e8] = pv; ps += pv;
;       }
;       u32x4 u;
;       u[0] = pk2(pv8[0], pv8[1]); u[1] = pk2(pv8[2], pv8[3]); u[2] = pk2(pv8[4], pv8[5]); u[3] = pk2(pv8[6], pv8[7]);
;       const bf16x8 pfg = __builtin_bit_cast(bf16x8, u);
; #pragma unroll
;       for (int dt = 0; dt < 4; ++dt) {
;         bf16x8 a = *(const bf16x8*)(sV + vro + dt * 4096 + (((4 * k2 + 2 * s2 + h) ^ vsw) << 4));
;         o[dt] = MFMA(a, pfg, o[dt]);
;       }
;       __builtin_amdgcn_sched_barrier(0);
;     }
;     l_run += ps;
;     asm volatile("s_waitcnt vmcnt(4)" ::: "memory");
;     if (MODE == 1 && tid < 16) *(f32x4*)(fct + ((kt + 1) & 3) * 64 + tid * 4) = rf;
;     if (MODE == 1) {
;       const int v = __all((qkb - flast) < (m_run - 160.f)) ? 1 : 0;
;       if (lane == 0) votes[(kt & 1) * 8 + wave] = v;
;     }
;     asm volatile("s_waitcnt lgkmcnt(0)" ::: "memory");
;     __builtin_amdgcn_s_barrier();
;     asm volatile("" ::: "memory");
;     sc[0] = sn[0]; sc[1] = sn[1]; bw = bwn;
	v_mfma_f32_32x32x16_bf16 v[96:111], v[232:235], v[136:139], v[96:111]
	v_add_u32_e32 v216, v252, v179
	ds_read_b128 v[232:235], v216 offset:8192
	v_fma_f32 v8, v84, s33, -v206
	v_fma_f32 v10, v85, s33, -v206
	v_exp_f32_e32 v8, v8
	v_exp_f32_e32 v10, v10
	v_bfe_i32 v9, v169, v186, 1
	v_bfe_i32 v11, v169, v187, 1
	v_and_b32_e32 v85, v9, v8
	v_and_b32_e32 v84, v11, v10
	s_waitcnt lgkmcnt(7)
	v_mfma_f32_32x32x16_bf16 v[96:111], v[236:239], v[140:143], v[96:111]
	v_add_u32_e32 v216, v252, v180
	ds_read_b128 v[236:239], v216 offset:8192
	v_fma_f32 v8, v86, s33, -v206
	v_fma_f32 v10, v87, s33, -v206
	v_exp_f32_e32 v8, v8
	v_exp_f32_e32 v10, v10
	v_bfe_i32 v9, v169, v188, 1
	v_bfe_i32 v11, v169, v189, 1
	v_and_b32_e32 v87, v9, v8
	v_and_b32_e32 v86, v11, v10
	v_cvt_pk_bf16_f32 v8, v81, v80
	v_cvt_pk_bf16_f32 v9, v83, v82
	v_cvt_pk_bf16_f32 v10, v85, v84
	v_cvt_pk_bf16_f32 v11, v87, v86
	v_add_u32_e32 v217, v211, v202
	s_waitcnt lgkmcnt(7)
	s_nop 0
	v_mfma_f32_32x32x16_bf16 v[64:79], v[240:243], v[8:11], v[64:79]
	ds_read_b128 v[240:243], v217 offset:16384
	v_add_f32_e32 v253, v168, v81
	v_add_f32_e32 v253, v253, v80
	s_waitcnt lgkmcnt(7)
	v_mfma_f32_32x32x16_bf16 v[48:63], v[244:247], v[8:11], v[48:63]
	ds_read_b128 v[244:247], v217 offset:20480
	v_add_f32_e32 v253, v253, v83
	v_add_f32_e32 v253, v253, v82
	s_waitcnt lgkmcnt(7)
	v_mfma_f32_32x32x16_bf16 v[32:47], v[248:251], v[8:11], v[32:47]
	ds_read_b128 v[248:251], v217 offset:24576
	v_add_f32_e32 v253, v253, v85
	v_add_f32_e32 v253, v253, v84
	s_waitcnt lgkmcnt(7)
	v_mfma_f32_32x32x16_bf16 v[16:31], v[212:215], v[8:11], v[16:31]
	ds_read_b128 v[212:215], v217 offset:28672
	v_add_f32_e32 v253, v253, v87
	v_add_f32_e32 v12, v253, v86
	s_waitcnt lgkmcnt(7)
	v_mfma_f32_32x32x16_bf16 v[96:111], v[224:227], v[144:147], v[96:111]
	v_fma_f32 v4, v88, s33, -v206
	v_fma_f32 v6, v89, s33, -v206
	v_exp_f32_e32 v4, v4
	v_exp_f32_e32 v6, v6
	v_bfe_i32 v5, v169, v191, 1
	v_bfe_i32 v7, v169, v192, 1
	v_and_b32_e32 v14, v5, v4
	v_and_b32_e32 v13, v7, v6
	s_waitcnt lgkmcnt(6)
	v_mfma_f32_32x32x16_bf16 v[96:111], v[228:231], v[148:151], v[96:111]
	v_fma_f32 v4, v90, s33, -v206
	v_fma_f32 v6, v91, s33, -v206
	v_exp_f32_e32 v4, v4
	v_exp_f32_e32 v6, v6
	v_bfe_i32 v5, v169, v193, 1
	v_bfe_i32 v7, v169, v194, 1
	v_and_b32_e32 v80, v5, v4
	v_and_b32_e32 v15, v7, v6
	s_waitcnt lgkmcnt(5)
	v_mfma_f32_32x32x16_bf16 v[96:111], v[232:235], v[152:155], v[96:111]
	v_fma_f32 v4, v92, s33, -v206
	v_fma_f32 v6, v93, s33, -v206
	v_exp_f32_e32 v4, v4
	v_exp_f32_e32 v6, v6
	v_bfe_i32 v5, v169, v195, 1
	v_bfe_i32 v7, v169, v196, 1
	v_and_b32_e32 v82, v5, v4
	v_and_b32_e32 v81, v7, v6
	s_waitcnt lgkmcnt(4)
	v_mfma_f32_32x32x16_bf16 v[96:111], v[236:239], v[156:159], v[96:111]
	v_fma_f32 v4, v94, s33, -v206
	v_fma_f32 v6, v95, s33, -v206
	v_exp_f32_e32 v4, v4
	v_exp_f32_e32 v6, v6
	v_bfe_i32 v5, v169, v197, 1
	v_bfe_i32 v7, v169, v198, 1
	v_and_b32_e32 v84, v5, v4
	v_and_b32_e32 v83, v7, v6
	v_cvt_pk_bf16_f32 v4, v14, v13
	v_cvt_pk_bf16_f32 v5, v80, v15
	v_cvt_pk_bf16_f32 v6, v82, v81
	v_cvt_pk_bf16_f32 v7, v84, v83
	s_waitcnt lgkmcnt(3)
	s_nop 0
	v_mfma_f32_32x32x16_bf16 v[64:79], v[240:243], v[4:7], v[64:79]
	s_waitcnt lgkmcnt(2)
	v_mfma_f32_32x32x16_bf16 v[48:63], v[244:247], v[4:7], v[48:63]
	s_waitcnt lgkmcnt(1)
	v_mfma_f32_32x32x16_bf16 v[32:47], v[248:251], v[4:7], v[32:47]
	v_add_f32_e32 v0, v12, v14
	v_add_f32_e32 v0, v0, v13
	v_add_f32_e32 v0, v0, v80
	v_add_f32_e32 v0, v0, v15
	v_add_f32_e32 v0, v0, v82
	v_add_f32_e32 v0, v0, v81
	s_waitcnt lgkmcnt(0)
	v_mfma_f32_32x32x16_bf16 v[16:31], v[212:215], v[4:7], v[16:31]
	v_add_f32_e32 v0, v0, v84
	v_add_f32_e32 v0, v0, v83
	s_waitcnt vmcnt(4)
	s_waitcnt lgkmcnt(0)
	s_barrier
	s_add_i32 s14, s14, 0x8000
	v_add_f32_e32 v182, v182, v0
	s_cmp_lg_u32 s12, s13
	s_cbranch_scc0 .LBB0_489
	v_mov_b64_e32 v[80:81], v[96:97]
	v_mov_b64_e32 v[82:83], v[98:99]
	v_mov_b64_e32 v[84:85], v[100:101]
	v_mov_b64_e32 v[86:87], v[102:103]
	v_mov_b64_e32 v[88:89], v[104:105]
	v_mov_b64_e32 v[90:91], v[106:107]
	v_mov_b64_e32 v[92:93], v[108:109]
	v_mov_b64_e32 v[94:95], v[110:111]
	v_mov_b64_e32 v[96:97], v[112:113]
	v_mov_b64_e32 v[98:99], v[114:115]
	v_mov_b64_e32 v[100:101], v[116:117]
	v_mov_b64_e32 v[102:103], v[118:119]
	v_mov_b64_e32 v[104:105], v[120:121]
	v_mov_b64_e32 v[106:107], v[122:123]
	v_mov_b64_e32 v[108:109], v[124:125]
	v_mov_b64_e32 v[110:111], v[126:127]
	s_waitcnt vmcnt(4)
	v_mov_b64_e32 v[168:169], v[2:3]
	s_branch .LBB0_492
